# P0 adaLN GEMV k-loop: dummy loads prefetch the next iteration's 16 w_ada rows into cache while the current chunk computes
# speedup vs baseline: 1.0295x; 1.0088x over previous
; #define LAS __attribute__((address_space(3)))
; __global__ void __launch_bounds__(512, 2) mega(Params P) {
;     ...
;             for (int k4 = ks * 128; k4 < ks * 128 + 128; k4 += 4) {
;                 const float w0 = wp[(size_t)k4 * 6144], w1 = wp[(size_t)(k4 + 1) * 6144], w2 = wp[(size_t)(k4 + 2) * 6144], w3 = wp[(size_t)(k4 + 3) * 6144];
; #pragma unroll
;                 for (int b = 0; b < 24; ++b) { const f32x4 sv = *(LAS const f32x4*)(sc + b * 1024 + k4); acc[b] += (sv[0] * w0 + sv[1] * w1) + (sv[2] * w2 + sv[3] * w3); }
.LBB0_22:
	s_mov_b32 s5, 0xfffa6000
	v_add_co_u32_e32 v0, vcc, s5, v24
	s_mov_b32 s5, 0xfffac000
	s_nop 0
	v_addc_co_u32_e32 v1, vcc, -1, v25, vcc
	global_load_dword v64, v[0:1], off
	v_add_co_u32_e32 v0, vcc, s5, v24
	v_add_u32_e32 v76, 16, v76
	s_nop 0
	v_addc_co_u32_e32 v1, vcc, -1, v25, vcc
	global_load_dword v66, v[0:1], off
	v_add_co_u32_e32 v0, vcc, s26, v24
	s_nop 1
	v_addc_co_u32_e32 v1, vcc, -1, v25, vcc
	global_load_dword v68, v[0:1], off
	v_add_co_u32_e32 v0, vcc, s27, v24
	s_nop 1
	v_addc_co_u32_e32 v1, vcc, -1, v25, vcc
	global_load_dword v16, v[0:1], off
	ds_read_b128 v[50:53], v75
	ds_read_b128 v[8:11], v75 offset:16
	ds_read_b128 v[4:7], v75 offset:32
	ds_read_b128 v[0:3], v75 offset:48
	ds_read_b128 v[54:57], v75 offset:4096
	s_waitcnt lgkmcnt(4)
	v_mov_b32_e32 v30, v50
	s_waitcnt lgkmcnt(0)
	v_mov_b32_e32 v31, v54
	v_mov_b32_e32 v54, v51
	s_waitcnt vmcnt(2)
	v_pk_mul_f32 v[50:51], v[66:67], v[54:55] op_sel_hi:[0,1]
	v_pk_fma_f32 v[30:31], v[64:65], v[30:31], v[50:51] op_sel_hi:[0,1,1]
	v_mov_b32_e32 v51, v56
	v_mov_b32_e32 v56, v53
	v_mov_b32_e32 v50, v52
	s_waitcnt vmcnt(0)
	v_pk_mul_f32 v[52:53], v[16:17], v[56:57] op_sel_hi:[0,1]
	v_pk_fma_f32 v[50:51], v[68:69], v[50:51], v[52:53] op_sel_hi:[0,1,1]
	v_pk_add_f32 v[30:31], v[30:31], v[50:51]
	ds_read_b128 v[50:53], v75 offset:8192
	ds_read_b128 v[54:57], v75 offset:12288
	v_pk_add_f32 v[62:63], v[26:27], v[30:31]
	s_waitcnt lgkmcnt(1)
	v_mov_b32_e32 v26, v50
	s_waitcnt lgkmcnt(0)
	v_mov_b32_e32 v27, v54
	v_mov_b32_e32 v54, v51
	v_pk_mul_f32 v[30:31], v[66:67], v[54:55] op_sel_hi:[0,1]
	v_pk_fma_f32 v[26:27], v[64:65], v[26:27], v[30:31] op_sel_hi:[0,1,1]
	v_mov_b32_e32 v31, v56
	v_mov_b32_e32 v56, v53
	v_mov_b32_e32 v30, v52
	v_pk_mul_f32 v[50:51], v[16:17], v[56:57] op_sel_hi:[0,1]
	v_pk_fma_f32 v[30:31], v[68:69], v[30:31], v[50:51] op_sel_hi:[0,1,1]
	v_pk_add_f32 v[26:27], v[26:27], v[30:31]
	s_nop 0
	v_pk_add_f32 v[58:59], v[28:29], v[26:27]
	ds_read_b128 v[26:29], v75 offset:16384
	ds_read_b128 v[50:53], v75 offset:20480
	s_waitcnt lgkmcnt(1)
	v_mov_b32_e32 v30, v26
	s_waitcnt lgkmcnt(0)
	v_mov_b32_e32 v31, v50
	v_mov_b32_e32 v50, v27
	v_pk_mul_f32 v[26:27], v[66:67], v[50:51] op_sel_hi:[0,1]
	v_pk_fma_f32 v[26:27], v[64:65], v[30:31], v[26:27] op_sel_hi:[0,1,1]
	v_mov_b32_e32 v31, v52
	v_mov_b32_e32 v52, v29
	v_mov_b32_e32 v30, v28
	v_pk_mul_f32 v[28:29], v[16:17], v[52:53] op_sel_hi:[0,1]
	v_pk_fma_f32 v[28:29], v[68:69], v[30:31], v[28:29] op_sel_hi:[0,1,1]
	v_pk_add_f32 v[26:27], v[26:27], v[28:29]
	s_nop 0
	v_pk_add_f32 v[56:57], v[32:33], v[26:27]
	ds_read_b128 v[26:29], v75 offset:24576
	ds_read_b128 v[30:33], v75 offset:28672
	s_waitcnt lgkmcnt(1)
	v_mov_b32_e32 v50, v26
	s_waitcnt lgkmcnt(0)
	v_mov_b32_e32 v51, v30
	v_mov_b32_e32 v30, v27
	v_pk_mul_f32 v[26:27], v[66:67], v[30:31] op_sel_hi:[0,1]
	v_mov_b32_e32 v31, v32
	v_mov_b32_e32 v32, v29
	v_mov_b32_e32 v30, v28
	v_pk_mul_f32 v[28:29], v[16:17], v[32:33] op_sel_hi:[0,1]
	v_pk_fma_f32 v[26:27], v[64:65], v[50:51], v[26:27] op_sel_hi:[0,1,1]
	v_pk_fma_f32 v[28:29], v[68:69], v[30:31], v[28:29] op_sel_hi:[0,1,1]
	v_pk_add_f32 v[26:27], v[26:27], v[28:29]
	s_nop 0
	v_pk_add_f32 v[54:55], v[34:35], v[26:27]
	ds_read_b128 v[26:29], v75 offset:32768
	ds_read_b128 v[30:33], v75 offset:36864
	s_waitcnt lgkmcnt(1)
	v_mov_b32_e32 v34, v26
	s_waitcnt lgkmcnt(0)
	v_mov_b32_e32 v35, v30
	v_mov_b32_e32 v30, v27
	v_pk_mul_f32 v[26:27], v[66:67], v[30:31] op_sel_hi:[0,1]
	v_mov_b32_e32 v31, v32
	v_mov_b32_e32 v32, v29
	v_mov_b32_e32 v30, v28
	v_pk_mul_f32 v[28:29], v[16:17], v[32:33] op_sel_hi:[0,1]
	v_pk_fma_f32 v[26:27], v[64:65], v[34:35], v[26:27] op_sel_hi:[0,1,1]
	v_pk_fma_f32 v[28:29], v[68:69], v[30:31], v[28:29] op_sel_hi:[0,1,1]
	v_pk_add_f32 v[26:27], v[26:27], v[28:29]
	s_nop 0
	v_pk_add_f32 v[52:53], v[36:37], v[26:27]
	ds_read_b128 v[26:29], v75 offset:40960
	ds_read_b128 v[30:33], v75 offset:45056
	s_waitcnt lgkmcnt(1)
	v_mov_b32_e32 v34, v26
	s_waitcnt lgkmcnt(0)
	v_mov_b32_e32 v35, v30
	v_mov_b32_e32 v30, v27
	v_pk_mul_f32 v[26:27], v[66:67], v[30:31] op_sel_hi:[0,1]
	v_mov_b32_e32 v31, v32
	v_mov_b32_e32 v32, v29
	v_mov_b32_e32 v30, v28
	v_pk_mul_f32 v[28:29], v[16:17], v[32:33] op_sel_hi:[0,1]
	v_pk_fma_f32 v[26:27], v[64:65], v[34:35], v[26:27] op_sel_hi:[0,1,1]
	v_pk_fma_f32 v[28:29], v[68:69], v[30:31], v[28:29] op_sel_hi:[0,1,1]
	v_pk_add_f32 v[26:27], v[26:27], v[28:29]
	s_nop 0
	v_pk_add_f32 v[50:51], v[40:41], v[26:27]
	ds_read_b128 v[26:29], v75 offset:49152
	ds_read_b128 v[30:33], v75 offset:53248
	s_waitcnt lgkmcnt(1)
	v_mov_b32_e32 v34, v26
	s_waitcnt lgkmcnt(0)
	v_mov_b32_e32 v35, v30
	v_mov_b32_e32 v30, v27
	v_pk_mul_f32 v[26:27], v[66:67], v[30:31] op_sel_hi:[0,1]
	v_mov_b32_e32 v31, v32
	v_mov_b32_e32 v32, v29
	v_mov_b32_e32 v30, v28
	v_pk_mul_f32 v[28:29], v[16:17], v[32:33] op_sel_hi:[0,1]
	v_pk_fma_f32 v[26:27], v[64:65], v[34:35], v[26:27] op_sel_hi:[0,1,1]
	v_pk_fma_f32 v[28:29], v[68:69], v[30:31], v[28:29] op_sel_hi:[0,1,1]
	v_pk_add_f32 v[26:27], v[26:27], v[28:29]
	s_nop 0
	v_pk_add_f32 v[42:43], v[42:43], v[26:27]
	ds_read_b128 v[26:29], v75 offset:57344
	ds_read_b128 v[30:33], v75 offset:61440
	s_waitcnt lgkmcnt(1)
	v_mov_b32_e32 v34, v26
	s_waitcnt lgkmcnt(0)
	v_mov_b32_e32 v35, v30
	v_mov_b32_e32 v30, v27
	v_pk_mul_f32 v[26:27], v[66:67], v[30:31] op_sel_hi:[0,1]
	v_mov_b32_e32 v31, v32
	v_mov_b32_e32 v32, v29
	v_mov_b32_e32 v30, v28
	v_pk_mul_f32 v[28:29], v[16:17], v[32:33] op_sel_hi:[0,1]
	v_pk_fma_f32 v[26:27], v[64:65], v[34:35], v[26:27] op_sel_hi:[0,1,1]
	v_pk_fma_f32 v[28:29], v[68:69], v[30:31], v[28:29] op_sel_hi:[0,1,1]
	v_pk_add_f32 v[26:27], v[26:27], v[28:29]
	v_add_u32_e32 v28, 0x10000, v75
	v_add_u32_e32 v32, 0x11000, v75
	ds_read_b128 v[28:31], v28
	ds_read_b128 v[32:35], v32
	v_pk_add_f32 v[26:27], v[44:45], v[26:27]
	s_waitcnt lgkmcnt(1)
; #define LAS __attribute__((address_space(3)))
; __global__ void __launch_bounds__(512, 2) mega(Params P) {
;     ...
;             for (int k4 = ks * 128; k4 < ks * 128 + 128; k4 += 4) {
;                 const float w0 = wp[(size_t)k4 * 6144], w1 = wp[(size_t)(k4 + 1) * 6144], w2 = wp[(size_t)(k4 + 2) * 6144], w3 = wp[(size_t)(k4 + 3) * 6144];
; #pragma unroll
;                 for (int b = 0; b < 24; ++b) { const f32x4 sv = *(LAS const f32x4*)(sc + b * 1024 + k4); acc[b] += (sv[0] * w0 + sv[1] * w1) + (sv[2] * w2 + sv[3] * w3); }
	v_mov_b32_e32 v36, v28
	s_waitcnt lgkmcnt(0)
	v_mov_b32_e32 v37, v32
	v_mov_b32_e32 v32, v29
	v_pk_mul_f32 v[28:29], v[66:67], v[32:33] op_sel_hi:[0,1]
	v_mov_b32_e32 v33, v34
	v_mov_b32_e32 v34, v31
	v_mov_b32_e32 v32, v30
	v_pk_mul_f32 v[30:31], v[16:17], v[34:35] op_sel_hi:[0,1]
	v_pk_fma_f32 v[28:29], v[64:65], v[36:37], v[28:29] op_sel_hi:[0,1,1]
	v_pk_fma_f32 v[30:31], v[68:69], v[32:33], v[30:31] op_sel_hi:[0,1,1]
	v_pk_add_f32 v[28:29], v[28:29], v[30:31]
	v_add_u32_e32 v30, 0x12000, v75
	v_add_u32_e32 v34, 0x13000, v75
	ds_read_b128 v[30:33], v30
	ds_read_b128 v[34:37], v34
	v_pk_add_f32 v[28:29], v[48:49], v[28:29]
	v_mov_b32_e32 v48, v8
	s_waitcnt lgkmcnt(1)
	v_mov_b32_e32 v40, v30
	s_waitcnt lgkmcnt(0)
	v_mov_b32_e32 v41, v34
	v_mov_b32_e32 v34, v31
	v_pk_mul_f32 v[30:31], v[66:67], v[34:35] op_sel_hi:[0,1]
	v_mov_b32_e32 v35, v36
	v_mov_b32_e32 v36, v33
	v_mov_b32_e32 v34, v32
	v_pk_mul_f32 v[32:33], v[16:17], v[36:37] op_sel_hi:[0,1]
	v_pk_fma_f32 v[30:31], v[64:65], v[40:41], v[30:31] op_sel_hi:[0,1,1]
	v_pk_fma_f32 v[32:33], v[68:69], v[34:35], v[32:33] op_sel_hi:[0,1,1]
	v_pk_add_f32 v[30:31], v[30:31], v[32:33]
	v_add_u32_e32 v32, 0x14000, v75
	v_add_u32_e32 v36, 0x15000, v75
	v_pk_add_f32 v[30:31], v[46:47], v[30:31]
	ds_read_b128 v[32:35], v32
	ds_read_b128 v[44:47], v36
	s_waitcnt lgkmcnt(1)
	v_mov_b32_e32 v36, v32
	s_waitcnt lgkmcnt(0)
	v_mov_b32_e32 v37, v44
	v_mov_b32_e32 v44, v33
	v_pk_mul_f32 v[32:33], v[66:67], v[44:45] op_sel_hi:[0,1]
	v_pk_fma_f32 v[32:33], v[64:65], v[36:37], v[32:33] op_sel_hi:[0,1,1]
	v_mov_b32_e32 v37, v46
	v_mov_b32_e32 v46, v35
	v_mov_b32_e32 v36, v34
	v_pk_mul_f32 v[34:35], v[16:17], v[46:47] op_sel_hi:[0,1]
	v_pk_fma_f32 v[34:35], v[68:69], v[36:37], v[34:35] op_sel_hi:[0,1,1]
	v_pk_add_f32 v[32:33], v[32:33], v[34:35]
	v_add_u32_e32 v34, 0x16000, v75
	ds_read_b128 v[34:37], v34
	v_pk_add_f32 v[32:33], v[38:39], v[32:33]
	v_mov_b32_e32 v65, v66
	v_mov_b32_e32 v69, v16
	v_mov_b32_e32 v67, v68
	s_waitcnt lgkmcnt(0)
	v_mul_f32_e32 v38, v66, v35
	v_pk_fma_f32 v[38:39], v[64:65], v[34:35], v[38:39] op_sel_hi:[1,1,0]
	v_mul_f32_e32 v34, v16, v37
	v_pk_fma_f32 v[40:41], v[68:69], v[36:37], v[34:35] op_sel_hi:[1,1,0]
	v_add_u32_e32 v34, 0x17000, v75
	ds_read_b128 v[34:37], v34
	v_mov_b32_e32 v65, v16
	s_waitcnt lgkmcnt(0)
	v_mov_b32_e32 v44, v35
	v_mov_b32_e32 v35, v37
	v_mov_b32_e32 v45, v36
	v_pk_mul_f32 v[34:35], v[64:65], v[34:35]
	v_add_co_u32_e32 v36, vcc, s28, v24
	v_pk_fma_f32 v[34:35], v[66:67], v[44:45], v[34:35]
	s_nop 0
	v_addc_co_u32_e32 v37, vcc, -1, v25, vcc
	v_mov_b32_e32 v39, v34
	v_mov_b32_e32 v41, v35
	v_pk_add_f32 v[34:35], v[38:39], v[40:41]
	v_add_co_u32_e32 v38, vcc, s29, v24
	global_load_dword v36, v[36:37], off
	s_nop 0
	v_addc_co_u32_e32 v39, vcc, -1, v25, vcc
	v_add_co_u32_e32 v40, vcc, s30, v24
	global_load_dword v38, v[38:39], off
	s_nop 0
	v_addc_co_u32_e32 v41, vcc, -1, v25, vcc
	v_add_co_u32_e32 v44, vcc, s31, v24
	global_load_dword v40, v[40:41], off
	s_nop 0
	v_addc_co_u32_e32 v45, vcc, -1, v25, vcc
	global_load_dword v16, v[44:45], off
	ds_read_b128 v[44:47], v75 offset:4112
	v_pk_add_f32 v[34:35], v[60:61], v[34:35]
	s_waitcnt lgkmcnt(0)
	v_mov_b32_e32 v49, v44
	v_mov_b32_e32 v44, v9
	s_waitcnt vmcnt(2)
	v_pk_mul_f32 v[8:9], v[38:39], v[44:45] op_sel_hi:[0,1]
	v_mov_b32_e32 v45, v46
	v_mov_b32_e32 v46, v11
	v_mov_b32_e32 v44, v10
	v_pk_fma_f32 v[8:9], v[36:37], v[48:49], v[8:9] op_sel_hi:[0,1,1]
	s_waitcnt vmcnt(0)
	v_pk_mul_f32 v[10:11], v[16:17], v[46:47] op_sel_hi:[0,1]
	v_pk_fma_f32 v[10:11], v[40:41], v[44:45], v[10:11] op_sel_hi:[0,1,1]
	v_pk_add_f32 v[8:9], v[8:9], v[10:11]
	s_nop 0
	v_pk_add_f32 v[48:49], v[62:63], v[8:9]
	ds_read_b128 v[8:11], v75 offset:8208
	ds_read_b128 v[44:47], v75 offset:12304
	s_waitcnt lgkmcnt(1)
	v_mov_b32_e32 v60, v8
	s_waitcnt lgkmcnt(0)
	v_mov_b32_e32 v61, v44
	v_mov_b32_e32 v44, v9
	v_pk_mul_f32 v[8:9], v[38:39], v[44:45] op_sel_hi:[0,1]
	v_mov_b32_e32 v45, v46
	v_mov_b32_e32 v46, v11
	v_mov_b32_e32 v44, v10
	v_pk_mul_f32 v[10:11], v[16:17], v[46:47] op_sel_hi:[0,1]
	v_pk_fma_f32 v[8:9], v[36:37], v[60:61], v[8:9] op_sel_hi:[0,1,1]
	v_pk_fma_f32 v[10:11], v[40:41], v[44:45], v[10:11] op_sel_hi:[0,1,1]
	v_pk_add_f32 v[8:9], v[8:9], v[10:11]
	s_nop 0
	v_pk_add_f32 v[60:61], v[58:59], v[8:9]
	ds_read_b128 v[8:11], v75 offset:16400
	ds_read_b128 v[44:47], v75 offset:20496
	s_waitcnt lgkmcnt(1)
	v_mov_b32_e32 v58, v8
	s_waitcnt lgkmcnt(0)
	v_mov_b32_e32 v59, v44
	v_mov_b32_e32 v44, v9
	v_pk_mul_f32 v[8:9], v[38:39], v[44:45] op_sel_hi:[0,1]
	v_mov_b32_e32 v45, v46
	v_mov_b32_e32 v46, v11
	v_mov_b32_e32 v44, v10
	v_pk_mul_f32 v[10:11], v[16:17], v[46:47] op_sel_hi:[0,1]
	v_pk_fma_f32 v[8:9], v[36:37], v[58:59], v[8:9] op_sel_hi:[0,1,1]
	v_pk_fma_f32 v[10:11], v[40:41], v[44:45], v[10:11] op_sel_hi:[0,1,1]
	v_pk_add_f32 v[8:9], v[8:9], v[10:11]
	s_nop 0
	v_pk_add_f32 v[62:63], v[56:57], v[8:9]
	ds_read_b128 v[8:11], v75 offset:24592
	ds_read_b128 v[44:47], v75 offset:28688
	s_waitcnt lgkmcnt(1)
	v_mov_b32_e32 v56, v8
	s_waitcnt lgkmcnt(0)
	v_mov_b32_e32 v57, v44
	v_mov_b32_e32 v44, v9
	v_pk_mul_f32 v[8:9], v[38:39], v[44:45] op_sel_hi:[0,1]
	v_mov_b32_e32 v45, v46
	v_mov_b32_e32 v46, v11
	v_mov_b32_e32 v44, v10
	v_pk_mul_f32 v[10:11], v[16:17], v[46:47] op_sel_hi:[0,1]
	v_pk_fma_f32 v[8:9], v[36:37], v[56:57], v[8:9] op_sel_hi:[0,1,1]
	v_pk_fma_f32 v[10:11], v[40:41], v[44:45], v[10:11] op_sel_hi:[0,1,1]
	v_pk_add_f32 v[8:9], v[8:9], v[10:11]
	s_nop 0
	v_pk_add_f32 v[64:65], v[54:55], v[8:9]
	ds_read_b128 v[8:11], v75 offset:32784
	ds_read_b128 v[44:47], v75 offset:36880
	s_waitcnt lgkmcnt(1)
	v_mov_b32_e32 v54, v8
	s_waitcnt lgkmcnt(0)
; #define LAS __attribute__((address_space(3)))
; __global__ void __launch_bounds__(512, 2) mega(Params P) {
;     ...
;             for (int k4 = ks * 128; k4 < ks * 128 + 128; k4 += 4) {
;                 const float w0 = wp[(size_t)k4 * 6144], w1 = wp[(size_t)(k4 + 1) * 6144], w2 = wp[(size_t)(k4 + 2) * 6144], w3 = wp[(size_t)(k4 + 3) * 6144];
; #pragma unroll
;                 for (int b = 0; b < 24; ++b) { const f32x4 sv = *(LAS const f32x4*)(sc + b * 1024 + k4); acc[b] += (sv[0] * w0 + sv[1] * w1) + (sv[2] * w2 + sv[3] * w3); }
	v_mov_b32_e32 v55, v44
	v_mov_b32_e32 v44, v9
	v_pk_mul_f32 v[8:9], v[38:39], v[44:45] op_sel_hi:[0,1]
	v_mov_b32_e32 v45, v46
	v_mov_b32_e32 v46, v11
	v_mov_b32_e32 v44, v10
	v_pk_mul_f32 v[10:11], v[16:17], v[46:47] op_sel_hi:[0,1]
	v_pk_fma_f32 v[8:9], v[36:37], v[54:55], v[8:9] op_sel_hi:[0,1,1]
	v_pk_fma_f32 v[10:11], v[40:41], v[44:45], v[10:11] op_sel_hi:[0,1,1]
	v_pk_add_f32 v[8:9], v[8:9], v[10:11]
	s_nop 0
	v_pk_add_f32 v[66:67], v[52:53], v[8:9]
	ds_read_b128 v[8:11], v75 offset:40976
	ds_read_b128 v[44:47], v75 offset:45072
	s_waitcnt lgkmcnt(1)
	v_mov_b32_e32 v52, v8
	s_waitcnt lgkmcnt(0)
	v_mov_b32_e32 v53, v44
	v_mov_b32_e32 v44, v9
	v_pk_mul_f32 v[8:9], v[38:39], v[44:45] op_sel_hi:[0,1]
	v_mov_b32_e32 v45, v46
	v_mov_b32_e32 v46, v11
	v_mov_b32_e32 v44, v10
	v_pk_mul_f32 v[10:11], v[16:17], v[46:47] op_sel_hi:[0,1]
	v_pk_fma_f32 v[8:9], v[36:37], v[52:53], v[8:9] op_sel_hi:[0,1,1]
	v_pk_fma_f32 v[10:11], v[40:41], v[44:45], v[10:11] op_sel_hi:[0,1,1]
	v_pk_add_f32 v[8:9], v[8:9], v[10:11]
	s_nop 0
	v_pk_add_f32 v[8:9], v[50:51], v[8:9]
	ds_read_b128 v[44:47], v75 offset:49168
	ds_read_b128 v[50:53], v75 offset:53264
	s_waitcnt lgkmcnt(1)
	v_mov_b32_e32 v10, v44
	s_waitcnt lgkmcnt(0)
	v_mov_b32_e32 v11, v50
	v_mov_b32_e32 v50, v45
	v_pk_mul_f32 v[44:45], v[38:39], v[50:51] op_sel_hi:[0,1]
	v_pk_fma_f32 v[10:11], v[36:37], v[10:11], v[44:45] op_sel_hi:[0,1,1]
	v_mov_b32_e32 v45, v52
	v_mov_b32_e32 v52, v47
	v_mov_b32_e32 v44, v46
	v_pk_mul_f32 v[46:47], v[16:17], v[52:53] op_sel_hi:[0,1]
	v_pk_fma_f32 v[44:45], v[40:41], v[44:45], v[46:47] op_sel_hi:[0,1,1]
	v_pk_add_f32 v[10:11], v[10:11], v[44:45]
	s_nop 0
	v_pk_add_f32 v[10:11], v[42:43], v[10:11]
	ds_read_b128 v[42:45], v75 offset:57360
	ds_read_b128 v[50:53], v75 offset:61456
	s_waitcnt lgkmcnt(1)
	v_mov_b32_e32 v46, v42
	s_waitcnt lgkmcnt(0)
	v_mov_b32_e32 v47, v50
	v_mov_b32_e32 v50, v43
	v_pk_mul_f32 v[42:43], v[38:39], v[50:51] op_sel_hi:[0,1]
	v_pk_fma_f32 v[42:43], v[36:37], v[46:47], v[42:43] op_sel_hi:[0,1,1]
	v_mov_b32_e32 v47, v52
	v_mov_b32_e32 v52, v45
	v_mov_b32_e32 v46, v44
	v_pk_mul_f32 v[44:45], v[16:17], v[52:53] op_sel_hi:[0,1]
	v_pk_fma_f32 v[44:45], v[40:41], v[46:47], v[44:45] op_sel_hi:[0,1,1]
	v_pk_add_f32 v[42:43], v[42:43], v[44:45]
	s_nop 0
	v_pk_add_f32 v[44:45], v[26:27], v[42:43]
	v_add_u32_e32 v26, 0x10010, v75
	ds_read_b128 v[50:53], v26
	v_add_u32_e32 v26, 0x11010, v75
	ds_read_b128 v[54:57], v26
	s_waitcnt lgkmcnt(1)
	v_mov_b32_e32 v26, v50
	s_waitcnt lgkmcnt(0)
	v_mov_b32_e32 v27, v54
	v_mov_b32_e32 v54, v51
	v_pk_mul_f32 v[42:43], v[38:39], v[54:55] op_sel_hi:[0,1]
	v_pk_fma_f32 v[26:27], v[36:37], v[26:27], v[42:43] op_sel_hi:[0,1,1]
	v_mov_b32_e32 v43, v56
	v_mov_b32_e32 v56, v53
	v_mov_b32_e32 v42, v52
	v_pk_mul_f32 v[46:47], v[16:17], v[56:57] op_sel_hi:[0,1]
	v_pk_fma_f32 v[42:43], v[40:41], v[42:43], v[46:47] op_sel_hi:[0,1,1]
	v_pk_add_f32 v[26:27], v[26:27], v[42:43]
	v_add_u32_e32 v37, 0x13010, v75
	v_pk_add_f32 v[46:47], v[28:29], v[26:27]
	v_add_u32_e32 v26, 0x12010, v75
	ds_read_b128 v[26:29], v26
	ds_read_b128 v[50:53], v37
	s_waitcnt lgkmcnt(1)
	v_mov_b32_e32 v42, v26
	s_waitcnt lgkmcnt(0)
	v_mov_b32_e32 v43, v50
	v_mov_b32_e32 v50, v27
	v_pk_mul_f32 v[26:27], v[38:39], v[50:51] op_sel_hi:[0,1]
	v_pk_fma_f32 v[26:27], v[36:37], v[42:43], v[26:27] op_sel_hi:[0,1,1]
	v_mov_b32_e32 v43, v52
	v_mov_b32_e32 v52, v29
	v_mov_b32_e32 v42, v28
	v_pk_mul_f32 v[28:29], v[16:17], v[52:53] op_sel_hi:[0,1]
	v_pk_fma_f32 v[28:29], v[40:41], v[42:43], v[28:29] op_sel_hi:[0,1,1]
	v_pk_add_f32 v[26:27], v[26:27], v[28:29]
	v_add_u32_e32 v37, 0x15010, v75
	v_pk_add_f32 v[30:31], v[30:31], v[26:27]
	v_add_u32_e32 v26, 0x14010, v75
	ds_read_b128 v[26:29], v26
	ds_read_b128 v[50:53], v37
	s_waitcnt lgkmcnt(1)
	v_mov_b32_e32 v42, v26
	s_waitcnt lgkmcnt(0)
	v_mov_b32_e32 v43, v50
	v_mov_b32_e32 v50, v27
	v_pk_mul_f32 v[26:27], v[38:39], v[50:51] op_sel_hi:[0,1]
	v_pk_fma_f32 v[26:27], v[36:37], v[42:43], v[26:27] op_sel_hi:[0,1,1]
	v_mov_b32_e32 v43, v52
	v_mov_b32_e32 v52, v29
	v_mov_b32_e32 v42, v28
	v_pk_mul_f32 v[28:29], v[16:17], v[52:53] op_sel_hi:[0,1]
	v_pk_fma_f32 v[28:29], v[40:41], v[42:43], v[28:29] op_sel_hi:[0,1,1]
	v_pk_add_f32 v[26:27], v[26:27], v[28:29]
	v_mov_b32_e32 v37, v38
	v_pk_add_f32 v[50:51], v[32:33], v[26:27]
	v_add_u32_e32 v26, 0x16010, v75
	ds_read_b128 v[26:29], v26
	v_mov_b32_e32 v41, v16
	v_mov_b32_e32 v39, v40
	s_waitcnt lgkmcnt(0)
	v_mul_f32_e32 v32, v38, v27
	v_pk_fma_f32 v[32:33], v[36:37], v[26:27], v[32:33] op_sel_hi:[1,1,0]
	v_mul_f32_e32 v26, v16, v29
	v_pk_fma_f32 v[42:43], v[40:41], v[28:29], v[26:27] op_sel_hi:[1,1,0]
	v_add_u32_e32 v26, 0x17010, v75
	ds_read_b128 v[26:29], v26
	v_mov_b32_e32 v37, v16
	s_waitcnt lgkmcnt(0)
	v_mov_b32_e32 v40, v27
	v_mov_b32_e32 v27, v29
	v_mov_b32_e32 v41, v28
	v_pk_mul_f32 v[26:27], v[36:37], v[26:27]
	s_nop 0
	v_pk_fma_f32 v[26:27], v[38:39], v[40:41], v[26:27]
	s_nop 0
	v_mov_b32_e32 v33, v26
	v_mov_b32_e32 v43, v27
	v_pk_add_f32 v[26:27], v[32:33], v[42:43]
	v_mov_b32_e32 v32, v4
	v_pk_add_f32 v[52:53], v[34:35], v[26:27]
	v_add_co_u32_e32 v26, vcc, s36, v24
	s_nop 1
	v_addc_co_u32_e32 v27, vcc, -1, v25, vcc
	global_load_dword v54, v[26:27], off
	v_add_co_u32_e32 v26, vcc, s37, v24
	s_nop 1
	v_addc_co_u32_e32 v27, vcc, -1, v25, vcc
	global_load_dword v56, v[26:27], off
	v_add_co_u32_e32 v26, vcc, s38, v24
	s_nop 1
	v_addc_co_u32_e32 v27, vcc, -1, v25, vcc
	global_load_dword v58, v[26:27], off
	v_add_co_u32_e32 v26, vcc, s39, v24
	s_nop 1
	v_addc_co_u32_e32 v27, vcc, -1, v25, vcc
	global_load_dword v16, v[26:27], off
	ds_read_b128 v[26:29], v75 offset:4128
	s_waitcnt lgkmcnt(0)
; #define LAS __attribute__((address_space(3)))
; __global__ void __launch_bounds__(512, 2) mega(Params P) {
;     ...
;             for (int k4 = ks * 128; k4 < ks * 128 + 128; k4 += 4) {
;                 const float w0 = wp[(size_t)k4 * 6144], w1 = wp[(size_t)(k4 + 1) * 6144], w2 = wp[(size_t)(k4 + 2) * 6144], w3 = wp[(size_t)(k4 + 3) * 6144];
; #pragma unroll
;                 for (int b = 0; b < 24; ++b) { const f32x4 sv = *(LAS const f32x4*)(sc + b * 1024 + k4); acc[b] += (sv[0] * w0 + sv[1] * w1) + (sv[2] * w2 + sv[3] * w3); }
	v_mov_b32_e32 v33, v26
	v_mov_b32_e32 v26, v5
	s_waitcnt vmcnt(2)
	v_pk_mul_f32 v[4:5], v[56:57], v[26:27] op_sel_hi:[0,1]
	v_mov_b32_e32 v27, v28
	v_mov_b32_e32 v28, v7
	v_mov_b32_e32 v26, v6
	v_pk_fma_f32 v[4:5], v[54:55], v[32:33], v[4:5] op_sel_hi:[0,1,1]
	s_waitcnt vmcnt(0)
	v_pk_mul_f32 v[6:7], v[16:17], v[28:29] op_sel_hi:[0,1]
	v_pk_fma_f32 v[6:7], v[58:59], v[26:27], v[6:7] op_sel_hi:[0,1,1]
	v_pk_add_f32 v[4:5], v[4:5], v[6:7]
	s_nop 0
	v_pk_add_f32 v[26:27], v[48:49], v[4:5]
	ds_read_b128 v[4:7], v75 offset:8224
	ds_read_b128 v[32:35], v75 offset:12320
	s_waitcnt lgkmcnt(1)
	v_mov_b32_e32 v28, v4
	s_waitcnt lgkmcnt(0)
	v_mov_b32_e32 v29, v32
	v_mov_b32_e32 v32, v5
	v_pk_mul_f32 v[4:5], v[56:57], v[32:33] op_sel_hi:[0,1]
	v_pk_fma_f32 v[4:5], v[54:55], v[28:29], v[4:5] op_sel_hi:[0,1,1]
	v_mov_b32_e32 v29, v34
	v_mov_b32_e32 v34, v7
	v_mov_b32_e32 v28, v6
	v_pk_mul_f32 v[6:7], v[16:17], v[34:35] op_sel_hi:[0,1]
	v_pk_fma_f32 v[6:7], v[58:59], v[28:29], v[6:7] op_sel_hi:[0,1,1]
	v_pk_add_f32 v[4:5], v[4:5], v[6:7]
	s_nop 0
	v_pk_add_f32 v[28:29], v[60:61], v[4:5]
	ds_read_b128 v[4:7], v75 offset:16416
	ds_read_b128 v[32:35], v75 offset:20512
	s_waitcnt lgkmcnt(1)
	v_mov_b32_e32 v36, v4
	s_waitcnt lgkmcnt(0)
	v_mov_b32_e32 v37, v32
	v_mov_b32_e32 v32, v5
	v_pk_mul_f32 v[4:5], v[56:57], v[32:33] op_sel_hi:[0,1]
	v_mov_b32_e32 v33, v34
	v_mov_b32_e32 v34, v7
	v_mov_b32_e32 v32, v6
	v_pk_mul_f32 v[6:7], v[16:17], v[34:35] op_sel_hi:[0,1]
	v_pk_fma_f32 v[4:5], v[54:55], v[36:37], v[4:5] op_sel_hi:[0,1,1]
	v_pk_fma_f32 v[6:7], v[58:59], v[32:33], v[6:7] op_sel_hi:[0,1,1]
	v_pk_add_f32 v[4:5], v[4:5], v[6:7]
	s_nop 0
	v_pk_add_f32 v[32:33], v[62:63], v[4:5]
	ds_read_b128 v[4:7], v75 offset:24608
	ds_read_b128 v[34:37], v75 offset:28704
	s_waitcnt lgkmcnt(1)
	v_mov_b32_e32 v38, v4
	s_waitcnt lgkmcnt(0)
	v_mov_b32_e32 v39, v34
	v_mov_b32_e32 v34, v5
	v_pk_mul_f32 v[4:5], v[56:57], v[34:35] op_sel_hi:[0,1]
	v_mov_b32_e32 v35, v36
	v_mov_b32_e32 v36, v7
	v_mov_b32_e32 v34, v6
	v_pk_mul_f32 v[6:7], v[16:17], v[36:37] op_sel_hi:[0,1]
	v_pk_fma_f32 v[4:5], v[54:55], v[38:39], v[4:5] op_sel_hi:[0,1,1]
	v_pk_fma_f32 v[6:7], v[58:59], v[34:35], v[6:7] op_sel_hi:[0,1,1]
	v_pk_add_f32 v[4:5], v[4:5], v[6:7]
	s_nop 0
	v_pk_add_f32 v[34:35], v[64:65], v[4:5]
	ds_read_b128 v[4:7], v75 offset:32800
	ds_read_b128 v[36:39], v75 offset:36896
	s_waitcnt lgkmcnt(1)
	v_mov_b32_e32 v40, v4
	s_waitcnt lgkmcnt(0)
	v_mov_b32_e32 v41, v36
	v_mov_b32_e32 v36, v5
	v_pk_mul_f32 v[4:5], v[56:57], v[36:37] op_sel_hi:[0,1]
	v_mov_b32_e32 v37, v38
	v_mov_b32_e32 v38, v7
	v_mov_b32_e32 v36, v6
	v_pk_mul_f32 v[6:7], v[16:17], v[38:39] op_sel_hi:[0,1]
	v_pk_fma_f32 v[4:5], v[54:55], v[40:41], v[4:5] op_sel_hi:[0,1,1]
	v_pk_fma_f32 v[6:7], v[58:59], v[36:37], v[6:7] op_sel_hi:[0,1,1]
	v_pk_add_f32 v[4:5], v[4:5], v[6:7]
	s_nop 0
	v_pk_add_f32 v[36:37], v[66:67], v[4:5]
	ds_read_b128 v[4:7], v75 offset:40992
	ds_read_b128 v[38:41], v75 offset:45088
	s_waitcnt lgkmcnt(1)
	v_mov_b32_e32 v42, v4
	s_waitcnt lgkmcnt(0)
	v_mov_b32_e32 v43, v38
	v_mov_b32_e32 v38, v5
	v_pk_mul_f32 v[4:5], v[56:57], v[38:39] op_sel_hi:[0,1]
	v_mov_b32_e32 v39, v40
	v_mov_b32_e32 v40, v7
	v_mov_b32_e32 v38, v6
	v_pk_mul_f32 v[6:7], v[16:17], v[40:41] op_sel_hi:[0,1]
	v_pk_fma_f32 v[4:5], v[54:55], v[42:43], v[4:5] op_sel_hi:[0,1,1]
	v_pk_fma_f32 v[6:7], v[58:59], v[38:39], v[6:7] op_sel_hi:[0,1,1]
	v_pk_add_f32 v[4:5], v[4:5], v[6:7]
	s_nop 0
	v_pk_add_f32 v[40:41], v[8:9], v[4:5]
	ds_read_b128 v[4:7], v75 offset:49184
	ds_read_b128 v[60:63], v75 offset:53280
	s_waitcnt lgkmcnt(1)
	v_mov_b32_e32 v8, v4
	s_waitcnt lgkmcnt(0)
	v_mov_b32_e32 v9, v60
	v_mov_b32_e32 v60, v5
	v_pk_mul_f32 v[4:5], v[56:57], v[60:61] op_sel_hi:[0,1]
	v_pk_fma_f32 v[4:5], v[54:55], v[8:9], v[4:5] op_sel_hi:[0,1,1]
	v_mov_b32_e32 v9, v62
	v_mov_b32_e32 v62, v7
	v_mov_b32_e32 v8, v6
	v_pk_mul_f32 v[6:7], v[16:17], v[62:63] op_sel_hi:[0,1]
	v_pk_fma_f32 v[6:7], v[58:59], v[8:9], v[6:7] op_sel_hi:[0,1,1]
	v_pk_add_f32 v[4:5], v[4:5], v[6:7]
	s_nop 0
	v_pk_add_f32 v[42:43], v[10:11], v[4:5]
	ds_read_b128 v[4:7], v75 offset:57376
	ds_read_b128 v[8:11], v75 offset:61472
	s_waitcnt lgkmcnt(1)
	v_mov_b32_e32 v38, v4
	s_waitcnt lgkmcnt(0)
	v_mov_b32_e32 v39, v8
	v_mov_b32_e32 v8, v5
	v_pk_mul_f32 v[4:5], v[56:57], v[8:9] op_sel_hi:[0,1]
	v_mov_b32_e32 v9, v10
	v_mov_b32_e32 v10, v7
	v_mov_b32_e32 v8, v6
	v_pk_mul_f32 v[6:7], v[16:17], v[10:11] op_sel_hi:[0,1]
	v_pk_fma_f32 v[4:5], v[54:55], v[38:39], v[4:5] op_sel_hi:[0,1,1]
	v_pk_fma_f32 v[6:7], v[58:59], v[8:9], v[6:7] op_sel_hi:[0,1,1]
	v_pk_add_f32 v[4:5], v[4:5], v[6:7]
	v_add_u32_e32 v8, 0x11020, v75
	v_pk_add_f32 v[44:45], v[44:45], v[4:5]
	v_add_u32_e32 v4, 0x10020, v75
	ds_read_b128 v[4:7], v4
	ds_read_b128 v[8:11], v8
	s_waitcnt lgkmcnt(1)
	v_mov_b32_e32 v38, v4
	s_waitcnt lgkmcnt(0)
	v_mov_b32_e32 v39, v8
	v_mov_b32_e32 v8, v5
	v_pk_mul_f32 v[4:5], v[56:57], v[8:9] op_sel_hi:[0,1]
	v_mov_b32_e32 v9, v10
	v_mov_b32_e32 v10, v7
	v_mov_b32_e32 v8, v6
	v_pk_mul_f32 v[6:7], v[16:17], v[10:11] op_sel_hi:[0,1]
	v_pk_fma_f32 v[4:5], v[54:55], v[38:39], v[4:5] op_sel_hi:[0,1,1]
	v_pk_fma_f32 v[6:7], v[58:59], v[8:9], v[6:7] op_sel_hi:[0,1,1]
	v_pk_add_f32 v[4:5], v[4:5], v[6:7]
	v_add_u32_e32 v8, 0x13020, v75
	v_pk_add_f32 v[48:49], v[46:47], v[4:5]
	v_add_u32_e32 v4, 0x12020, v75
	ds_read_b128 v[4:7], v4
	ds_read_b128 v[8:11], v8
	s_waitcnt lgkmcnt(1)
	v_mov_b32_e32 v38, v4
	s_waitcnt lgkmcnt(0)
; #define LAS __attribute__((address_space(3)))
; __global__ void __launch_bounds__(512, 2) mega(Params P) {
;     ...
;             for (int k4 = ks * 128; k4 < ks * 128 + 128; k4 += 4) {
;                 const float w0 = wp[(size_t)k4 * 6144], w1 = wp[(size_t)(k4 + 1) * 6144], w2 = wp[(size_t)(k4 + 2) * 6144], w3 = wp[(size_t)(k4 + 3) * 6144];
; #pragma unroll
;                 for (int b = 0; b < 24; ++b) { const f32x4 sv = *(LAS const f32x4*)(sc + b * 1024 + k4); acc[b] += (sv[0] * w0 + sv[1] * w1) + (sv[2] * w2 + sv[3] * w3); }
	v_mov_b32_e32 v39, v8
	v_mov_b32_e32 v8, v5
	v_pk_mul_f32 v[4:5], v[56:57], v[8:9] op_sel_hi:[0,1]
	v_mov_b32_e32 v9, v10
	v_mov_b32_e32 v10, v7
	v_mov_b32_e32 v8, v6
	v_pk_mul_f32 v[6:7], v[16:17], v[10:11] op_sel_hi:[0,1]
	v_pk_fma_f32 v[4:5], v[54:55], v[38:39], v[4:5] op_sel_hi:[0,1,1]
	v_pk_fma_f32 v[6:7], v[58:59], v[8:9], v[6:7] op_sel_hi:[0,1,1]
	v_pk_add_f32 v[4:5], v[4:5], v[6:7]
	v_add_u32_e32 v8, 0x15020, v75
	v_pk_add_f32 v[46:47], v[30:31], v[4:5]
	v_add_u32_e32 v4, 0x14020, v75
	ds_read_b128 v[4:7], v4
	ds_read_b128 v[8:11], v8
	s_waitcnt lgkmcnt(1)
	v_mov_b32_e32 v30, v4
	s_waitcnt lgkmcnt(0)
	v_mov_b32_e32 v31, v8
	v_mov_b32_e32 v8, v5
	v_pk_mul_f32 v[4:5], v[56:57], v[8:9] op_sel_hi:[0,1]
	v_mov_b32_e32 v9, v10
	v_mov_b32_e32 v10, v7
	v_mov_b32_e32 v8, v6
	v_pk_mul_f32 v[6:7], v[16:17], v[10:11] op_sel_hi:[0,1]
	v_pk_fma_f32 v[4:5], v[54:55], v[30:31], v[4:5] op_sel_hi:[0,1,1]
	v_pk_fma_f32 v[6:7], v[58:59], v[8:9], v[6:7] op_sel_hi:[0,1,1]
	v_pk_add_f32 v[4:5], v[4:5], v[6:7]
	v_mov_b32_e32 v55, v56
	v_pk_add_f32 v[38:39], v[50:51], v[4:5]
	v_add_u32_e32 v4, 0x16020, v75
	ds_read_b128 v[4:7], v4
	v_mov_b32_e32 v59, v16
	v_mov_b32_e32 v57, v58
	s_waitcnt lgkmcnt(0)
	v_mul_f32_e32 v8, v56, v5
	v_pk_fma_f32 v[8:9], v[54:55], v[4:5], v[8:9] op_sel_hi:[1,1,0]
	v_mul_f32_e32 v4, v16, v7
	v_pk_fma_f32 v[10:11], v[58:59], v[6:7], v[4:5] op_sel_hi:[1,1,0]
	v_add_u32_e32 v4, 0x17020, v75
	ds_read_b128 v[4:7], v4
	v_mov_b32_e32 v55, v16
	s_waitcnt lgkmcnt(0)
	v_mov_b32_e32 v30, v5
	v_mov_b32_e32 v5, v7
	v_mov_b32_e32 v31, v6
	v_pk_mul_f32 v[4:5], v[54:55], v[4:5]
	v_add_co_u32_e32 v6, vcc, s40, v24
	v_pk_fma_f32 v[4:5], v[56:57], v[30:31], v[4:5]
	s_nop 0
	v_addc_co_u32_e32 v7, vcc, -1, v25, vcc
	v_mov_b32_e32 v9, v4
	v_mov_b32_e32 v11, v5
	v_pk_add_f32 v[4:5], v[8:9], v[10:11]
	v_add_co_u32_e32 v8, vcc, s41, v24
	global_load_dword v6, v[6:7], off
	s_nop 0
	v_addc_co_u32_e32 v9, vcc, -1, v25, vcc
	v_add_co_u32_e32 v10, vcc, s42, v24
	global_load_dword v8, v[8:9], off
	s_nop 0
	v_addc_co_u32_e32 v11, vcc, -1, v25, vcc
	global_load_dword v30, v[10:11], off
	s_nop 0
	global_load_dword v10, v[24:25], off
	v_pk_add_f32 v[4:5], v[52:53], v[4:5]
	ds_read_b128 v[50:53], v75 offset:4144
	v_mov_b32_e32 v54, v0
	v_cmp_ge_i32_e32 vcc, v76, v70
	v_lshl_add_u64 v[24:25], v[24:25], 0, s[20:21]
	s_or_b64 s[52:53], vcc, s[52:53]
	s_waitcnt lgkmcnt(0)
	v_mov_b32_e32 v55, v50
	v_mov_b32_e32 v50, v1
	s_waitcnt vmcnt(2)
	v_pk_mul_f32 v[0:1], v[8:9], v[50:51] op_sel_hi:[0,1]
	v_mov_b32_e32 v51, v52
	v_mov_b32_e32 v52, v3
	v_mov_b32_e32 v50, v2
	s_waitcnt vmcnt(0)
	s_cmp_lg_u64 s[52:53], 0
	s_cbranch_scc1 .Lada_pf_skip
	s_mov_b32 s12, 0xfffa6000
	s_mov_b32 s13, -1
	s_mov_b64 s[14:15], 0x6000
	v_lshl_add_u64 v[190:191], v[24:25], 0, s[12:13]
	global_load_dword v192, v[190:191], off
	v_lshl_add_u64 v[190:191], v[190:191], 0, s[14:15]
	global_load_dword v192, v[190:191], off
	v_lshl_add_u64 v[190:191], v[190:191], 0, s[14:15]
	global_load_dword v192, v[190:191], off
	v_lshl_add_u64 v[190:191], v[190:191], 0, s[14:15]
	global_load_dword v192, v[190:191], off
	v_lshl_add_u64 v[190:191], v[190:191], 0, s[14:15]
	global_load_dword v192, v[190:191], off
	v_lshl_add_u64 v[190:191], v[190:191], 0, s[14:15]
	global_load_dword v192, v[190:191], off
	v_lshl_add_u64 v[190:191], v[190:191], 0, s[14:15]
	global_load_dword v192, v[190:191], off
	v_lshl_add_u64 v[190:191], v[190:191], 0, s[14:15]
	global_load_dword v192, v[190:191], off
	v_lshl_add_u64 v[190:191], v[190:191], 0, s[14:15]
	global_load_dword v192, v[190:191], off
	v_lshl_add_u64 v[190:191], v[190:191], 0, s[14:15]
	global_load_dword v192, v[190:191], off
	v_lshl_add_u64 v[190:191], v[190:191], 0, s[14:15]
	global_load_dword v192, v[190:191], off
	v_lshl_add_u64 v[190:191], v[190:191], 0, s[14:15]
	global_load_dword v192, v[190:191], off
	v_lshl_add_u64 v[190:191], v[190:191], 0, s[14:15]
	global_load_dword v192, v[190:191], off
	v_lshl_add_u64 v[190:191], v[190:191], 0, s[14:15]
	global_load_dword v192, v[190:191], off
	v_lshl_add_u64 v[190:191], v[190:191], 0, s[14:15]
	global_load_dword v192, v[190:191], off
	v_lshl_add_u64 v[190:191], v[190:191], 0, s[14:15]
	global_load_dword v192, v[190:191], off
.Lada_pf_skip:
	v_pk_mul_f32 v[2:3], v[10:11], v[52:53] op_sel_hi:[0,1]
	v_pk_fma_f32 v[0:1], v[6:7], v[54:55], v[0:1] op_sel_hi:[0,1,1]
	v_pk_fma_f32 v[2:3], v[30:31], v[50:51], v[2:3] op_sel_hi:[0,1,1]
	v_pk_add_f32 v[0:1], v[0:1], v[2:3]
	s_nop 0
	v_pk_add_f32 v[26:27], v[26:27], v[0:1]
	ds_read_b128 v[0:3], v75 offset:8240
	ds_read_b128 v[50:53], v75 offset:12336
	s_waitcnt lgkmcnt(1)
	v_mov_b32_e32 v54, v0
	s_waitcnt lgkmcnt(0)
	v_mov_b32_e32 v55, v50
	v_mov_b32_e32 v50, v1
	v_pk_mul_f32 v[0:1], v[8:9], v[50:51] op_sel_hi:[0,1]
	v_mov_b32_e32 v51, v52
	v_mov_b32_e32 v52, v3
	v_mov_b32_e32 v50, v2
	v_pk_mul_f32 v[2:3], v[10:11], v[52:53] op_sel_hi:[0,1]
	v_pk_fma_f32 v[0:1], v[6:7], v[54:55], v[0:1] op_sel_hi:[0,1,1]
	v_pk_fma_f32 v[2:3], v[30:31], v[50:51], v[2:3] op_sel_hi:[0,1,1]
	v_pk_add_f32 v[0:1], v[0:1], v[2:3]
	s_nop 0
	v_pk_add_f32 v[28:29], v[28:29], v[0:1]
	ds_read_b128 v[0:3], v75 offset:16432
	ds_read_b128 v[50:53], v75 offset:20528
	s_waitcnt lgkmcnt(1)
	v_mov_b32_e32 v54, v0
	s_waitcnt lgkmcnt(0)
	v_mov_b32_e32 v55, v50
	v_mov_b32_e32 v50, v1
	v_pk_mul_f32 v[0:1], v[8:9], v[50:51] op_sel_hi:[0,1]
	v_mov_b32_e32 v51, v52
	v_mov_b32_e32 v52, v3
	v_mov_b32_e32 v50, v2
	v_pk_mul_f32 v[2:3], v[10:11], v[52:53] op_sel_hi:[0,1]
	v_pk_fma_f32 v[0:1], v[6:7], v[54:55], v[0:1] op_sel_hi:[0,1,1]
	v_pk_fma_f32 v[2:3], v[30:31], v[50:51], v[2:3] op_sel_hi:[0,1,1]
	v_pk_add_f32 v[0:1], v[0:1], v[2:3]
	s_nop 0
	v_pk_add_f32 v[32:33], v[32:33], v[0:1]
	ds_read_b128 v[0:3], v75 offset:24624
	ds_read_b128 v[50:53], v75 offset:28720
	s_waitcnt lgkmcnt(1)
; #define LAS __attribute__((address_space(3)))
; __global__ void __launch_bounds__(512, 2) mega(Params P) {
;     ...
;             for (int k4 = ks * 128; k4 < ks * 128 + 128; k4 += 4) {
;                 const float w0 = wp[(size_t)k4 * 6144], w1 = wp[(size_t)(k4 + 1) * 6144], w2 = wp[(size_t)(k4 + 2) * 6144], w3 = wp[(size_t)(k4 + 3) * 6144];
; #pragma unroll
;                 for (int b = 0; b < 24; ++b) { const f32x4 sv = *(LAS const f32x4*)(sc + b * 1024 + k4); acc[b] += (sv[0] * w0 + sv[1] * w1) + (sv[2] * w2 + sv[3] * w3); }
	v_mov_b32_e32 v54, v0
	s_waitcnt lgkmcnt(0)
	v_mov_b32_e32 v55, v50
	v_mov_b32_e32 v50, v1
	v_pk_mul_f32 v[0:1], v[8:9], v[50:51] op_sel_hi:[0,1]
	v_mov_b32_e32 v51, v52
	v_mov_b32_e32 v52, v3
	v_mov_b32_e32 v50, v2
	v_pk_mul_f32 v[2:3], v[10:11], v[52:53] op_sel_hi:[0,1]
	v_pk_fma_f32 v[0:1], v[6:7], v[54:55], v[0:1] op_sel_hi:[0,1,1]
	v_pk_fma_f32 v[2:3], v[30:31], v[50:51], v[2:3] op_sel_hi:[0,1,1]
	v_pk_add_f32 v[0:1], v[0:1], v[2:3]
	s_nop 0
	v_pk_add_f32 v[34:35], v[34:35], v[0:1]
	ds_read_b128 v[0:3], v75 offset:32816
	ds_read_b128 v[50:53], v75 offset:36912
	s_waitcnt lgkmcnt(1)
	v_mov_b32_e32 v54, v0
	s_waitcnt lgkmcnt(0)
	v_mov_b32_e32 v55, v50
	v_mov_b32_e32 v50, v1
	v_pk_mul_f32 v[0:1], v[8:9], v[50:51] op_sel_hi:[0,1]
	v_mov_b32_e32 v51, v52
	v_mov_b32_e32 v52, v3
	v_mov_b32_e32 v50, v2
	v_pk_mul_f32 v[2:3], v[10:11], v[52:53] op_sel_hi:[0,1]
	v_pk_fma_f32 v[0:1], v[6:7], v[54:55], v[0:1] op_sel_hi:[0,1,1]
	v_pk_fma_f32 v[2:3], v[30:31], v[50:51], v[2:3] op_sel_hi:[0,1,1]
	v_pk_add_f32 v[0:1], v[0:1], v[2:3]
	s_nop 0
	v_pk_add_f32 v[36:37], v[36:37], v[0:1]
	ds_read_b128 v[0:3], v75 offset:41008
	ds_read_b128 v[50:53], v75 offset:45104
	s_waitcnt lgkmcnt(1)
	v_mov_b32_e32 v54, v0
	s_waitcnt lgkmcnt(0)
	v_mov_b32_e32 v55, v50
	v_mov_b32_e32 v50, v1
	v_pk_mul_f32 v[0:1], v[8:9], v[50:51] op_sel_hi:[0,1]
	v_mov_b32_e32 v51, v52
	v_mov_b32_e32 v52, v3
	v_mov_b32_e32 v50, v2
	v_pk_mul_f32 v[2:3], v[10:11], v[52:53] op_sel_hi:[0,1]
	v_pk_fma_f32 v[0:1], v[6:7], v[54:55], v[0:1] op_sel_hi:[0,1,1]
	v_pk_fma_f32 v[2:3], v[30:31], v[50:51], v[2:3] op_sel_hi:[0,1,1]
	v_pk_add_f32 v[0:1], v[0:1], v[2:3]
	s_nop 0
	v_pk_add_f32 v[40:41], v[40:41], v[0:1]
	ds_read_b128 v[0:3], v75 offset:49200
	ds_read_b128 v[50:53], v75 offset:53296
	s_waitcnt lgkmcnt(1)
	v_mov_b32_e32 v54, v0
	s_waitcnt lgkmcnt(0)
	v_mov_b32_e32 v55, v50
	v_mov_b32_e32 v50, v1
	v_pk_mul_f32 v[0:1], v[8:9], v[50:51] op_sel_hi:[0,1]
	v_mov_b32_e32 v51, v52
	v_mov_b32_e32 v52, v3
	v_mov_b32_e32 v50, v2
	v_pk_mul_f32 v[2:3], v[10:11], v[52:53] op_sel_hi:[0,1]
	v_pk_fma_f32 v[0:1], v[6:7], v[54:55], v[0:1] op_sel_hi:[0,1,1]
	v_pk_fma_f32 v[2:3], v[30:31], v[50:51], v[2:3] op_sel_hi:[0,1,1]
	v_pk_add_f32 v[0:1], v[0:1], v[2:3]
	s_nop 0
	v_pk_add_f32 v[42:43], v[42:43], v[0:1]
	ds_read_b128 v[0:3], v75 offset:57392
	ds_read_b128 v[50:53], v75 offset:61488
	s_waitcnt lgkmcnt(1)
	v_mov_b32_e32 v54, v0
	s_waitcnt lgkmcnt(0)
	v_mov_b32_e32 v55, v50
	v_mov_b32_e32 v50, v1
	v_pk_mul_f32 v[0:1], v[8:9], v[50:51] op_sel_hi:[0,1]
	v_mov_b32_e32 v51, v52
	v_mov_b32_e32 v52, v3
	v_mov_b32_e32 v50, v2
	v_pk_mul_f32 v[2:3], v[10:11], v[52:53] op_sel_hi:[0,1]
	v_pk_fma_f32 v[0:1], v[6:7], v[54:55], v[0:1] op_sel_hi:[0,1,1]
	v_pk_fma_f32 v[2:3], v[30:31], v[50:51], v[2:3] op_sel_hi:[0,1,1]
	v_pk_add_f32 v[0:1], v[0:1], v[2:3]
	v_add_u32_e32 v7, 0x11030, v75
	v_pk_add_f32 v[44:45], v[44:45], v[0:1]
	v_add_u32_e32 v0, 0x10030, v75
	ds_read_b128 v[0:3], v0
	ds_read_b128 v[50:53], v7
	s_waitcnt lgkmcnt(1)
	v_mov_b32_e32 v54, v0
	s_waitcnt lgkmcnt(0)
	v_mov_b32_e32 v55, v50
	v_mov_b32_e32 v50, v1
	v_pk_mul_f32 v[0:1], v[8:9], v[50:51] op_sel_hi:[0,1]
	v_mov_b32_e32 v51, v52
	v_mov_b32_e32 v52, v3
	v_mov_b32_e32 v50, v2
	v_pk_mul_f32 v[2:3], v[10:11], v[52:53] op_sel_hi:[0,1]
	v_pk_fma_f32 v[0:1], v[6:7], v[54:55], v[0:1] op_sel_hi:[0,1,1]
	v_pk_fma_f32 v[2:3], v[30:31], v[50:51], v[2:3] op_sel_hi:[0,1,1]
	v_pk_add_f32 v[0:1], v[0:1], v[2:3]
	v_add_u32_e32 v7, 0x13030, v75
	v_pk_add_f32 v[48:49], v[48:49], v[0:1]
	v_add_u32_e32 v0, 0x12030, v75
	ds_read_b128 v[0:3], v0
	ds_read_b128 v[50:53], v7
	s_waitcnt lgkmcnt(1)
	v_mov_b32_e32 v54, v0
	s_waitcnt lgkmcnt(0)
	v_mov_b32_e32 v55, v50
	v_mov_b32_e32 v50, v1
	v_pk_mul_f32 v[0:1], v[8:9], v[50:51] op_sel_hi:[0,1]
	v_mov_b32_e32 v51, v52
	v_mov_b32_e32 v52, v3
	v_mov_b32_e32 v50, v2
	v_pk_mul_f32 v[2:3], v[10:11], v[52:53] op_sel_hi:[0,1]
	v_pk_fma_f32 v[0:1], v[6:7], v[54:55], v[0:1] op_sel_hi:[0,1,1]
	v_pk_fma_f32 v[2:3], v[30:31], v[50:51], v[2:3] op_sel_hi:[0,1,1]
	v_pk_add_f32 v[0:1], v[0:1], v[2:3]
	s_nop 0
	v_pk_add_f32 v[46:47], v[46:47], v[0:1]
	v_add_u32_e32 v0, 0x14030, v75
	ds_read_b128 v[50:53], v0
	v_add_u32_e32 v0, 0x15030, v75
	ds_read_b128 v[0:3], v0
	s_waitcnt lgkmcnt(1)
	v_mov_b32_e32 v54, v50
	v_mov_b32_e32 v50, v52
	s_waitcnt lgkmcnt(0)
	v_mov_b32_e32 v55, v0
	v_mov_b32_e32 v0, v51
	v_mov_b32_e32 v51, v2
	v_mov_b32_e32 v2, v53
	v_pk_mul_f32 v[0:1], v[8:9], v[0:1] op_sel_hi:[0,1]
	v_pk_mul_f32 v[2:3], v[10:11], v[2:3] op_sel_hi:[0,1]
	v_pk_fma_f32 v[0:1], v[6:7], v[54:55], v[0:1] op_sel_hi:[0,1,1]
	v_pk_fma_f32 v[2:3], v[30:31], v[50:51], v[2:3] op_sel_hi:[0,1,1]
	v_pk_add_f32 v[0:1], v[0:1], v[2:3]
	v_mov_b32_e32 v7, v8
	v_pk_add_f32 v[38:39], v[38:39], v[0:1]
	v_add_u32_e32 v0, 0x16030, v75
	ds_read_b128 v[0:3], v0
	v_mov_b32_e32 v31, v10
	v_mov_b32_e32 v9, v30
	s_waitcnt lgkmcnt(0)
	v_mul_f32_e32 v16, v8, v1
	v_pk_fma_f32 v[0:1], v[6:7], v[0:1], v[16:17] op_sel_hi:[1,1,0]
	v_mul_f32_e32 v16, v10, v3
	v_add_u32_e32 v1, 0x17030, v75
	ds_read_b128 v[50:53], v1
	v_pk_fma_f32 v[2:3], v[30:31], v[2:3], v[16:17] op_sel_hi:[1,1,0]
	v_mov_b32_e32 v7, v10
	v_add_u32_e32 v75, 64, v75
	s_waitcnt lgkmcnt(0)
	v_mov_b32_e32 v30, v51
	v_mov_b32_e32 v51, v53
	v_mov_b32_e32 v31, v52
	v_pk_mul_f32 v[6:7], v[6:7], v[50:51]
	s_nop 0
	v_pk_fma_f32 v[6:7], v[8:9], v[30:31], v[6:7]
	s_nop 0
	v_mov_b32_e32 v1, v6
	v_mov_b32_e32 v3, v7
	v_pk_add_f32 v[0:1], v[0:1], v[2:3]
	s_nop 0
	v_pk_add_f32 v[60:61], v[4:5], v[0:1]
	s_andn2_b64 exec, exec, s[52:53]
	s_cbranch_execnz .LBB0_22
; DI unsigned pk2(float lo, float hi) { f32x2 v = {lo, hi}; bf16x2_t b = __builtin_convertvector(v, bf16x2_t); return __builtin_bit_cast(unsigned, b); }
; #define PIN(i) gptr(P.in[i])
; __global__ void __launch_bounds__(512, 2) mega(Params P) {
;     ...
;             }
;             __syncthreads();
; #pragma unroll
;             for (int b = 0; b < 24; ++b) sc[(ks * 24 + b) * 64 + cl0] = acc[b];
;             __syncthreads();
;             for (int idx = tid; idx < 24 * 64; idx += 512) {
;                 const int b = idx >> 6, cl = idx & 63;
;                 float sm = 0.f;
; #pragma unroll
;                 for (int q = 0; q < 8; ++q) sm += sc[(q * 24 + b) * 64 + cl];
;                 const float mv = sm + PIN(I_BADA)[(size_t)l * 6144 + cb * 64 + cl];
;                 MOD[((size_t)l * 24 + b) * 6144 + cb * 64 + cl] = mv;
;                 const int col = cb * 64 + cl;
;                 if (col < 1024) WSP(bf16_t, WS_SHM)[(size_t)(32 * (2 * l) + b) * 1024 + col] = (bf16_t)(pk2(mv, 0.f) & 0xffffu);
;                 else if (col >= 3072 && col < 4096) WSP(bf16_t, WS_SHM)[(size_t)(32 * (2 * l + 1) + b) * 1024 + (col - 3072)] = (bf16_t)(pk2(mv, 0.f) & 0xffffu);
	s_or_b64 exec, exec, s[52:53]
	s_barrier
	ds_write2st64_b32 v74, v26, v27 offset1:1
	ds_write2st64_b32 v74, v28, v29 offset0:2 offset1:3
	ds_write2st64_b32 v74, v32, v33 offset0:4 offset1:5
	ds_write2st64_b32 v74, v34, v35 offset0:6 offset1:7
	ds_write2st64_b32 v74, v36, v37 offset0:8 offset1:9
	ds_write2st64_b32 v74, v40, v41 offset0:10 offset1:11
	ds_write2st64_b32 v74, v42, v43 offset0:12 offset1:13
	ds_write2st64_b32 v74, v44, v45 offset0:14 offset1:15
	ds_write2st64_b32 v74, v48, v49 offset0:16 offset1:17
	ds_write2st64_b32 v74, v46, v47 offset0:18 offset1:19
	ds_write2st64_b32 v74, v38, v39 offset0:20 offset1:21
	ds_write2st64_b32 v74, v60, v61 offset0:22 offset1:23
	s_waitcnt lgkmcnt(0)
	s_barrier
	s_and_saveexec_b64 s[12:13], s[2:3]
	s_cbranch_execz .LBB0_15
	s_add_u32 s5, s84, s34
	s_addc_u32 s16, s85, s35
	s_mul_i32 s19, s22, 0x6000
	s_mul_hi_i32 s17, s22, 0x6000
	s_add_u32 s24, s5, s19
	s_addc_u32 s25, s16, s17
	s_and_b32 s5, s18, 0x3fffff0
	v_lshlrev_b32_e32 v16, 2, v14
	s_cmp_eq_u32 s5, 48
	v_lshl_add_u64 v[0:1], s[24:25], 0, v[16:17]
	v_or_b32_e32 v16, s4, v14
	s_cselect_b64 s[18:19], -1, 0
	s_lshl_b32 s45, s22, 6
	v_ashrrev_i32_e32 v7, 31, v16
	v_mov_b32_e32 v6, v16
	s_mul_hi_i32 s17, s22, 24
	s_mul_i32 s16, s22, 24
	s_or_b32 s46, s45, 32
	v_lshl_add_u64 v[2:3], v[18:19], 0, s[34:35]
	v_cmp_lt_i32_e64 s[4:5], s43, v16
	v_lshl_add_u64 v[4:5], v[16:17], 1, s[8:9]
	v_lshl_add_u64 v[6:7], v[6:7], 1, s[10:11]
	s_mov_b64 s[22:23], 0
	v_mov_b32_e32 v10, v12
	s_branch .LBB0_26
